# xcc_census at the start of phases A / E1 / E2: the sixteen counter loads issued together and waited for once
# speedup vs baseline: 1.0014x; 1.0014x over previous
.LBB0_35:
	v_readlane_b32 s2, v255, 46
	s_add_i32 s2, s2, -2
	s_mul_hi_i32 s3, s2, 0x92492493
	s_add_i32 s3, s3, s2
	s_lshr_b32 s4, s3, 31
	s_ashr_i32 s3, s3, 2
	s_add_i32 s6, s3, s4
	s_mov_b32 s4, s6
	v_writelane_b32 v255, s4, 47
	s_mul_i32 s3, s6, 7
	s_mov_b64 s[26:27], 0
	v_writelane_b32 v255, s5, 48
	s_sub_i32 s4, s2, s3
	v_writelane_b32 v255, s4, 49
	s_cmp_lt_i32 s4, 3
	s_mov_b64 s[4:5], 0
	v_writelane_b32 v255, s4, 50
	s_mov_b64 s[2:3], -1
	s_mov_b64 s[6:7], 0
	v_writelane_b32 v255, s5, 51
	s_cbranch_scc1 .LBB0_86
	v_readlane_b32 s2, v255, 49
	s_cmp_gt_i32 s2, 3
	s_cbranch_scc0 .LBB0_52
	s_cmp_gt_i32 s2, 4
	s_cbranch_scc0 .LBB0_53
	s_mov_b64 s[4:5], -1
	s_mov_b64 s[28:29], 0
	s_cmp_eq_u32 s2, 5
	s_cbranch_scc0 .LBB0_55
	v_readlane_b32 s2, v253, 23
	v_readlane_b32 s3, v253, 24
	v_mbcnt_lo_u32_b32 v0, -1, 0
	v_mbcnt_hi_u32_b32 v0, -1, v0
	v_readlane_b32 s30, v255, 45
	s_cmp_lt_i32 s30, 8
	v_readlane_b32 s36, v253, 2
	v_readlane_b32 s38, v253, 4
	v_readlane_b32 s37, v253, 3
	global_load_dword v1, v41, s[2:3] sc1
	v_readlane_b32 s2, v253, 49
	v_readlane_b32 s3, v253, 50
	s_nop 4
	global_load_dword v2, v41, s[2:3] sc1
	v_readlane_b32 s2, v253, 51
	v_readlane_b32 s3, v253, 52
	s_nop 4
	global_load_dword v3, v41, s[2:3] sc1
	v_readlane_b32 s2, v253, 53
	v_readlane_b32 s3, v253, 54
	s_nop 4
	global_load_dword v4, v41, s[2:3] sc1
	v_readlane_b32 s2, v253, 55
	v_readlane_b32 s3, v253, 56
	s_nop 4
	global_load_dword v5, v41, s[2:3] sc1
	v_readlane_b32 s2, v253, 57
	v_readlane_b32 s3, v253, 58
	s_nop 4
	global_load_dword v6, v41, s[2:3] sc1
	v_readlane_b32 s2, v253, 59
	v_readlane_b32 s3, v253, 60
	s_nop 4
	global_load_dword v7, v41, s[2:3] sc1
	v_readlane_b32 s2, v253, 61
	v_readlane_b32 s3, v253, 62
	s_nop 4
	global_load_dword v8, v41, s[2:3] sc1
	v_readlane_b32 s2, v253, 63
	v_readlane_b32 s3, v254, 0
	s_nop 4
	global_load_dword v9, v41, s[2:3] sc1
	v_readlane_b32 s2, v254, 1
	v_readlane_b32 s3, v254, 2
	s_nop 4
	global_load_dword v10, v41, s[2:3] sc1
	v_readlane_b32 s2, v254, 3
	v_readlane_b32 s3, v254, 4
	s_nop 4
	global_load_dword v11, v41, s[2:3] sc1
	v_readlane_b32 s2, v254, 5
	v_readlane_b32 s3, v254, 6
	s_nop 4
	global_load_dword v12, v41, s[2:3] sc1
	v_readlane_b32 s2, v254, 7
	v_readlane_b32 s3, v254, 8
	s_nop 4
	global_load_dword v13, v41, s[2:3] sc1
	v_readlane_b32 s2, v254, 9
	v_readlane_b32 s3, v254, 10
	s_nop 4
	global_load_dword v14, v41, s[2:3] sc1
	v_readlane_b32 s2, v254, 11
	v_readlane_b32 s3, v254, 12
	s_nop 4
	global_load_dword v15, v41, s[2:3] sc1
	v_readlane_b32 s2, v254, 13
	v_readlane_b32 s3, v254, 14
	s_nop 4
	global_load_dword v16, v41, s[2:3] sc1
	s_waitcnt vmcnt(0)
	v_readlane_b32 s39, v253, 5
	v_cmp_ne_u32_e32 vcc, 0, v1
	v_add_u32_e32 v17, v2, v1
	v_cmp_ne_u32_e64 s[4:5], 0, v2
	v_add_u32_e32 v17, v17, v3
	v_cmp_ne_u32_e64 s[6:7], 0, v3
	v_add_u32_e32 v17, v17, v4
	v_cmp_ne_u32_e64 s[8:9], 0, v4
	v_add_u32_e32 v17, v17, v5
	v_cmp_ne_u32_e64 s[10:11], 0, v5
	v_add_u32_e32 v17, v17, v6
	v_cmp_ne_u32_e64 s[12:13], 0, v6
	v_cmp_ne_u32_e64 s[14:15], 0, v7
	v_cmp_ne_u32_e64 s[16:17], 0, v8
	v_cmp_eq_u32_e64 s[18:19], 0, v9
	v_cmp_eq_u32_e64 s[20:21], 0, v10
	v_cmp_eq_u32_e64 s[22:23], 0, v11
	v_or_b32_e32 v18, v15, v14
	s_cselect_b64 s[2:3], -1, 0
	s_and_b64 s[2:3], s[2:3], vcc
	s_cmp_eq_u32 s30, 0
	s_cselect_b64 vcc, -1, 0
	s_cmp_eq_u32 s30, 1
	v_cndmask_b32_e32 v1, 0, v1, vcc
	s_cselect_b64 vcc, -1, 0
	v_cndmask_b32_e32 v1, v1, v2, vcc
	v_add_u32_e32 v2, v17, v7
	v_add_u32_e32 v2, v2, v8
	v_add_u32_e32 v2, v2, v9
	s_cmp_eq_u32 s30, 2
	v_add_u32_e32 v2, v2, v10
	s_cselect_b64 vcc, -1, 0
	s_cmp_eq_u32 s30, 3
	v_add_u32_e32 v2, v2, v11
	v_cndmask_b32_e32 v1, v1, v3, vcc
	s_cselect_b64 vcc, -1, 0
	s_cmp_eq_u32 s30, 4
	v_add_u32_e32 v2, v2, v12
	v_cndmask_b32_e32 v1, v1, v4, vcc
	s_cselect_b64 vcc, -1, 0
	s_cmp_eq_u32 s30, 5
	v_add_u32_e32 v2, v2, v13
	v_cndmask_b32_e32 v1, v1, v5, vcc
	s_cselect_b64 vcc, -1, 0
	s_cmp_eq_u32 s30, 6
	v_add_u32_e32 v2, v2, v14
	v_cndmask_b32_e32 v1, v1, v6, vcc
	s_cselect_b64 vcc, -1, 0
	s_cmp_eq_u32 s30, 7
	v_add_u32_e32 v2, v2, v15
	v_cndmask_b32_e32 v1, v1, v7, vcc
	s_cselect_b64 vcc, -1, 0
	v_cndmask_b32_e32 v1, v1, v8, vcc
	s_waitcnt vmcnt(0)
	v_or_b32_e32 v18, v18, v16
	v_or_b32_e32 v18, v13, v18
	v_or_b32_e32 v18, v12, v18
	v_add_u32_e32 v2, v2, v16
	v_cmp_eq_u32_e64 s[24:25], 0, v18
	v_cmp_eq_u32_e32 vcc, s38, v2
	s_and_b64 s[24:25], vcc, s[24:25]
	s_and_b64 s[22:23], s[24:25], s[22:23]
	s_and_b64 s[20:21], s[22:23], s[20:21]
	s_and_b64 s[18:19], s[20:21], s[18:19]
	s_and_b64 s[16:17], s[18:19], s[16:17]
	s_and_b64 s[14:15], s[16:17], s[14:15]
	s_and_b64 s[12:13], s[14:15], s[12:13]
	s_and_b64 s[10:11], s[12:13], s[10:11]
	s_and_b64 s[8:9], s[10:11], s[8:9]
	s_and_b64 s[6:7], s[8:9], s[6:7]
	s_and_b64 s[4:5], s[6:7], s[4:5]
	s_and_b64 vcc, s[4:5], s[2:3]
	v_cndmask_b32_e32 v38, 0, v1, vcc
	v_cmp_lt_i32_e32 vcc, 0, v38
	v_readlane_b32 s2, v255, 2
	s_nop 1
	v_mov_b32_e32 v39, s2
	s_cbranch_vccz .LBB0_41
	v_cvt_f32_u32_e32 v2, v1
	v_sub_u32_e32 v4, 0, v1
	v_add_u32_e32 v3, 63, v1
	v_rcp_iflag_f32_e32 v2, v2
	s_nop 0
	v_mul_f32_e32 v2, 0x4f7ffffe, v2
	v_cvt_u32_f32_e32 v2, v2
	v_mul_lo_u32 v4, v4, v2
	v_mul_hi_u32 v4, v2, v4
	v_add_u32_e32 v2, v2, v4
	v_mul_hi_u32 v2, v3, v2
	v_mul_lo_u32 v4, v2, v1
	v_sub_u32_e32 v3, v3, v4
	v_add_u32_e32 v5, 1, v2
	v_sub_u32_e32 v4, v3, v1
	v_cmp_ge_u32_e32 vcc, v3, v1
	s_nop 1
	v_cndmask_b32_e32 v2, v2, v5, vcc
	v_cndmask_b32_e32 v3, v3, v4, vcc
	v_add_u32_e32 v4, 1, v2
	v_cmp_ge_u32_e32 vcc, v3, v1
	s_nop 1
	v_cndmask_b32_e32 v39, v2, v4, vcc

.LBB0_56:
	v_readlane_b32 s2, v253, 23
	v_readlane_b32 s3, v253, 24
	v_mbcnt_lo_u32_b32 v0, -1, 0
	v_mbcnt_hi_u32_b32 v0, -1, v0
	v_readlane_b32 s28, v255, 45
	s_cmp_lt_i32 s28, 8
	s_nop 2
	global_load_dword v1, v41, s[2:3] sc1
	v_readlane_b32 s2, v253, 49
	v_readlane_b32 s3, v253, 50
	s_nop 4
	global_load_dword v2, v41, s[2:3] sc1
	v_readlane_b32 s2, v253, 51
	v_readlane_b32 s3, v253, 52
	s_nop 4
	global_load_dword v3, v41, s[2:3] sc1
	v_readlane_b32 s2, v253, 53
	v_readlane_b32 s3, v253, 54
	s_nop 4
	global_load_dword v4, v41, s[2:3] sc1
	v_readlane_b32 s2, v253, 55
	v_readlane_b32 s3, v253, 56
	s_nop 4
	global_load_dword v5, v41, s[2:3] sc1
	v_readlane_b32 s2, v253, 57
	v_readlane_b32 s3, v253, 58
	s_nop 4
	global_load_dword v6, v41, s[2:3] sc1
	v_readlane_b32 s2, v253, 59
	v_readlane_b32 s3, v253, 60
	s_nop 4
	global_load_dword v7, v41, s[2:3] sc1
	v_readlane_b32 s2, v253, 61
	v_readlane_b32 s3, v253, 62
	s_nop 4
	global_load_dword v8, v41, s[2:3] sc1
	v_readlane_b32 s2, v253, 63
	v_readlane_b32 s3, v254, 0
	s_nop 4
	global_load_dword v9, v41, s[2:3] sc1
	v_readlane_b32 s2, v254, 1
	v_readlane_b32 s3, v254, 2
	s_nop 4
	global_load_dword v10, v41, s[2:3] sc1
	v_readlane_b32 s2, v254, 3
	v_readlane_b32 s3, v254, 4
	s_nop 4
	global_load_dword v11, v41, s[2:3] sc1
	v_readlane_b32 s2, v254, 5
	v_readlane_b32 s3, v254, 6
	s_nop 4
	global_load_dword v12, v41, s[2:3] sc1
	v_readlane_b32 s2, v254, 7
	v_readlane_b32 s3, v254, 8
	s_nop 4
	global_load_dword v13, v41, s[2:3] sc1
	v_readlane_b32 s2, v254, 9
	v_readlane_b32 s3, v254, 10
	s_nop 4
	global_load_dword v14, v41, s[2:3] sc1
	v_readlane_b32 s2, v254, 11
	v_readlane_b32 s3, v254, 12
	s_nop 4
	global_load_dword v15, v41, s[2:3] sc1
	v_readlane_b32 s2, v254, 13
	v_readlane_b32 s3, v254, 14
	s_nop 4
	global_load_dword v16, v41, s[2:3] sc1
	s_waitcnt vmcnt(0)
	v_cmp_ne_u32_e32 vcc, 0, v1
	v_add_u32_e32 v17, v2, v1
	v_cmp_ne_u32_e64 s[4:5], 0, v2
	v_add_u32_e32 v17, v17, v3
	v_cmp_ne_u32_e64 s[6:7], 0, v3
	v_add_u32_e32 v17, v17, v4
	v_cmp_ne_u32_e64 s[8:9], 0, v4
	v_add_u32_e32 v17, v17, v5
	v_cmp_ne_u32_e64 s[10:11], 0, v5
	v_add_u32_e32 v17, v17, v6
	v_cmp_ne_u32_e64 s[12:13], 0, v6
	v_cmp_ne_u32_e64 s[14:15], 0, v7
	v_cmp_ne_u32_e64 s[16:17], 0, v8
	v_cmp_eq_u32_e64 s[18:19], 0, v9
	v_cmp_eq_u32_e64 s[20:21], 0, v10
	v_cmp_eq_u32_e64 s[22:23], 0, v11
	v_or_b32_e32 v18, v15, v14
	s_cselect_b64 s[2:3], -1, 0
	s_and_b64 s[2:3], s[2:3], vcc
	s_cmp_eq_u32 s28, 0
	s_cselect_b64 vcc, -1, 0
	s_cmp_eq_u32 s28, 1
	v_cndmask_b32_e32 v1, 0, v1, vcc
	s_cselect_b64 vcc, -1, 0
	v_cndmask_b32_e32 v1, v1, v2, vcc
	v_add_u32_e32 v2, v17, v7
	v_add_u32_e32 v2, v2, v8
	v_add_u32_e32 v2, v2, v9
	s_cmp_eq_u32 s28, 2
	v_add_u32_e32 v2, v2, v10
	s_cselect_b64 vcc, -1, 0
	s_cmp_eq_u32 s28, 3
	v_add_u32_e32 v2, v2, v11
	v_cndmask_b32_e32 v1, v1, v3, vcc
	s_cselect_b64 vcc, -1, 0
	s_cmp_eq_u32 s28, 4
	v_add_u32_e32 v2, v2, v12
	v_cndmask_b32_e32 v1, v1, v4, vcc
	s_cselect_b64 vcc, -1, 0
	s_cmp_eq_u32 s28, 5
	v_add_u32_e32 v2, v2, v13
	v_cndmask_b32_e32 v1, v1, v5, vcc
	s_cselect_b64 vcc, -1, 0
	s_cmp_eq_u32 s28, 6
	v_add_u32_e32 v2, v2, v14
	v_cndmask_b32_e32 v1, v1, v6, vcc
	s_cselect_b64 vcc, -1, 0
	s_cmp_eq_u32 s28, 7
	v_add_u32_e32 v2, v2, v15
	v_readlane_b32 s28, v253, 2
	v_cndmask_b32_e32 v1, v1, v7, vcc
	s_cselect_b64 vcc, -1, 0
	v_readlane_b32 s30, v253, 4
	v_cndmask_b32_e32 v1, v1, v8, vcc
	v_readlane_b32 s29, v253, 3
	v_readlane_b32 s31, v253, 5
	s_waitcnt vmcnt(0)
	v_or_b32_e32 v18, v18, v16
	v_or_b32_e32 v18, v13, v18
	v_or_b32_e32 v18, v12, v18
	v_add_u32_e32 v2, v2, v16
	v_cmp_eq_u32_e64 s[24:25], 0, v18
	v_cmp_eq_u32_e32 vcc, s30, v2
	s_and_b64 s[24:25], vcc, s[24:25]
	s_and_b64 s[22:23], s[24:25], s[22:23]
	s_and_b64 s[20:21], s[22:23], s[20:21]
	s_and_b64 s[18:19], s[20:21], s[18:19]
	s_and_b64 s[16:17], s[18:19], s[16:17]
	s_and_b64 s[14:15], s[16:17], s[14:15]
	s_and_b64 s[12:13], s[14:15], s[12:13]
	s_and_b64 s[10:11], s[12:13], s[10:11]
	s_and_b64 s[8:9], s[10:11], s[8:9]
	s_and_b64 s[6:7], s[8:9], s[6:7]
	s_and_b64 s[4:5], s[6:7], s[4:5]
	s_and_b64 vcc, s[4:5], s[2:3]
	v_cndmask_b32_e32 v2, 0, v1, vcc
	v_cmp_lt_i32_e32 vcc, 0, v2
	v_readlane_b32 s2, v255, 2
	v_accvgpr_write_b32 a156, v2
	s_nop 0
	v_mov_b32_e32 v8, s2
	s_cbranch_vccz .LBB0_58
	v_cvt_f32_u32_e32 v2, v1
	v_sub_u32_e32 v4, 0, v1
	v_add_u32_e32 v3, 63, v1
	v_rcp_iflag_f32_e32 v2, v2
	s_nop 0
	v_mul_f32_e32 v2, 0x4f7ffffe, v2
	v_cvt_u32_f32_e32 v2, v2
	s_nop 0
	v_readfirstlane_b32 s2, v2
	s_nop 1
	v_mul_lo_u32 v2, v4, s2
	v_mul_hi_u32 v2, s2, v2
	v_add_u32_e32 v2, s2, v2
	v_mul_hi_u32 v2, v3, v2
	v_mul_lo_u32 v4, v2, v1
	v_sub_u32_e32 v3, v3, v4
	v_add_u32_e32 v5, 1, v2
	v_sub_u32_e32 v4, v3, v1
	v_cmp_ge_u32_e32 vcc, v3, v1
	s_nop 1
	v_cndmask_b32_e32 v2, v2, v5, vcc
	v_cndmask_b32_e32 v3, v3, v4, vcc
	v_add_u32_e32 v4, 1, v2
	v_cmp_ge_u32_e32 vcc, v3, v1
	s_nop 1
	v_cndmask_b32_e32 v8, v2, v4, vcc

.LBB0_329:
	s_andn2_b64 vcc, exec, s[26:27]
	s_cbranch_vccnz .LBB0_544
	v_readlane_b32 s2, v253, 23
	v_readlane_b32 s3, v253, 24
	v_mbcnt_lo_u32_b32 v0, -1, 0
	v_mbcnt_hi_u32_b32 v0, -1, v0
	v_readlane_b32 s25, v255, 45
	s_cmp_lt_i32 s25, 8
	v_readlane_b32 s36, v253, 2
	v_readlane_b32 s38, v253, 4
	v_readlane_b32 s37, v253, 3
	global_load_dword v1, v41, s[2:3] sc1
	v_readlane_b32 s2, v253, 49
	v_readlane_b32 s3, v253, 50
	s_nop 4
	global_load_dword v2, v41, s[2:3] sc1
	v_readlane_b32 s2, v253, 51
	v_readlane_b32 s3, v253, 52
	s_nop 4
	global_load_dword v3, v41, s[2:3] sc1
	v_readlane_b32 s2, v253, 53
	v_readlane_b32 s3, v253, 54
	s_nop 4
	global_load_dword v4, v41, s[2:3] sc1
	v_readlane_b32 s2, v253, 55
	v_readlane_b32 s3, v253, 56
	s_nop 4
	global_load_dword v5, v41, s[2:3] sc1
	v_readlane_b32 s2, v253, 57
	v_readlane_b32 s3, v253, 58
	s_nop 4
	global_load_dword v6, v41, s[2:3] sc1
	v_readlane_b32 s2, v253, 59
	v_readlane_b32 s3, v253, 60
	s_nop 4
	global_load_dword v7, v41, s[2:3] sc1
	v_readlane_b32 s2, v253, 61
	v_readlane_b32 s3, v253, 62
	s_nop 4
	global_load_dword v8, v41, s[2:3] sc1
	v_readlane_b32 s2, v253, 63
	v_readlane_b32 s3, v254, 0
	s_nop 4
	global_load_dword v9, v41, s[2:3] sc1
	v_readlane_b32 s2, v254, 1
	v_readlane_b32 s3, v254, 2
	s_nop 4
	global_load_dword v10, v41, s[2:3] sc1
	v_readlane_b32 s2, v254, 3
	v_readlane_b32 s3, v254, 4
	s_nop 4
	global_load_dword v11, v41, s[2:3] sc1
	v_readlane_b32 s2, v254, 5
	v_readlane_b32 s3, v254, 6
	s_nop 4
	global_load_dword v12, v41, s[2:3] sc1
	v_readlane_b32 s2, v254, 7
	v_readlane_b32 s3, v254, 8
	s_nop 4
	global_load_dword v13, v41, s[2:3] sc1
	v_readlane_b32 s2, v254, 9
	v_readlane_b32 s3, v254, 10
	s_nop 4
	global_load_dword v14, v41, s[2:3] sc1
	v_readlane_b32 s2, v254, 11
	v_readlane_b32 s3, v254, 12
	s_nop 4
	global_load_dword v15, v41, s[2:3] sc1
	v_readlane_b32 s2, v254, 13
	v_readlane_b32 s3, v254, 14
	s_nop 4
	global_load_dword v16, v41, s[2:3] sc1
	s_waitcnt vmcnt(0)
	v_readlane_b32 s39, v253, 5
	v_readfirstlane_b32 s6, v1
	v_readfirstlane_b32 s7, v2
	v_readfirstlane_b32 s10, v3
	v_readfirstlane_b32 s12, v4
	v_readfirstlane_b32 s14, v5
	v_readfirstlane_b32 s16, v6
	v_readfirstlane_b32 s18, v7
	v_readfirstlane_b32 s20, v8
	v_readfirstlane_b32 s21, v9
	v_readfirstlane_b32 s22, v10
	v_readfirstlane_b32 s24, v11
	v_readfirstlane_b32 s28, v12
	v_readfirstlane_b32 s29, v13
	v_readfirstlane_b32 s30, v14
	v_readfirstlane_b32 s31, v15
	s_cselect_b64 s[2:3], -1, 0
	s_cmp_lg_u32 s6, 0
	s_cselect_b64 s[4:5], -1, 0
	s_and_b64 s[2:3], s[2:3], s[4:5]
	s_cmp_eq_u32 s25, 0
	s_cselect_b32 s8, s6, 0
	s_add_i32 s6, s7, s6
	s_cmp_lg_u32 s7, 0
	s_cselect_b64 s[4:5], -1, 0
	s_cmp_eq_u32 s25, 1
	s_cselect_b32 s7, s7, s8
	s_add_i32 s6, s6, s10
	s_cmp_lg_u32 s10, 0
	s_cselect_b64 s[8:9], -1, 0
	s_cmp_eq_u32 s25, 2
	s_cselect_b32 s7, s10, s7
	s_add_i32 s6, s6, s12
	s_cmp_lg_u32 s12, 0
	s_cselect_b64 s[10:11], -1, 0
	s_cmp_eq_u32 s25, 3
	s_cselect_b32 s7, s12, s7
	s_add_i32 s6, s6, s14
	s_cmp_lg_u32 s14, 0
	s_cselect_b64 s[12:13], -1, 0
	s_cmp_eq_u32 s25, 4
	s_cselect_b32 s7, s14, s7
	s_add_i32 s6, s6, s16
	s_cmp_lg_u32 s16, 0
	s_cselect_b64 s[14:15], -1, 0
	s_cmp_eq_u32 s25, 5
	s_cselect_b32 s7, s16, s7
	s_add_i32 s6, s6, s18
	s_cmp_lg_u32 s18, 0
	s_cselect_b64 s[16:17], -1, 0
	s_cmp_eq_u32 s25, 6
	s_cselect_b32 s7, s18, s7
	s_add_i32 s23, s6, s20
	s_cmp_lg_u32 s20, 0
	s_cselect_b64 s[18:19], -1, 0
	s_cmp_eq_u32 s25, 7
	s_cselect_b32 s6, s20, s7
	s_add_i32 s7, s23, s21
	s_cmp_eq_u32 s21, 0
	s_cselect_b64 s[20:21], -1, 0
	s_add_i32 s7, s7, s22
	s_cmp_eq_u32 s22, 0
	s_cselect_b64 s[22:23], -1, 0
	s_add_i32 s7, s7, s24
	s_cmp_eq_u32 s24, 0
	s_cselect_b64 s[24:25], -1, 0
	s_add_i32 s7, s7, s28
	s_add_i32 s7, s7, s29
	s_add_i32 s7, s7, s30
	s_add_i32 s7, s7, s31
	s_waitcnt vmcnt(0)
	v_readfirstlane_b32 s34, v16
	s_add_i32 s7, s7, s34
	s_cmp_eq_u32 s7, s38
	s_cselect_b64 s[26:27], -1, 0
	s_or_b32 s7, s31, s30
	s_or_b32 s7, s7, s34
	s_or_b32 s7, s29, s7
	s_or_b32 s7, s28, s7
	s_cmp_eq_u32 s7, 0
	s_cselect_b64 s[28:29], -1, 0
	s_and_b64 s[26:27], s[26:27], s[28:29]
	s_and_b64 s[24:25], s[26:27], s[24:25]
	s_and_b64 s[22:23], s[24:25], s[22:23]
	s_and_b64 s[20:21], s[22:23], s[20:21]
	s_and_b64 s[18:19], s[20:21], s[18:19]
	s_and_b64 s[16:17], s[18:19], s[16:17]
	s_and_b64 s[14:15], s[16:17], s[14:15]
	s_and_b64 s[12:13], s[14:15], s[12:13]
	s_and_b64 s[10:11], s[12:13], s[10:11]
	s_and_b64 s[8:9], s[10:11], s[8:9]
	s_and_b64 s[4:5], s[8:9], s[4:5]
	s_and_b64 s[2:3], s[4:5], s[2:3]
	s_and_b64 s[2:3], s[2:3], exec
	s_cselect_b32 s40, s6, 0
	s_cmp_gt_i32 s40, 0
	s_cselect_b64 s[4:5], -1, 0
	s_cmp_lt_i32 s40, 1
	s_cselect_b64 s[22:23], -1, 0
	s_mov_b64 s[2:3], -1
	s_and_b64 vcc, exec, s[22:23]
	s_cbranch_vccz .LBB0_334
	v_readlane_b32 s2, v254, 24
	v_readlane_b32 s3, v254, 25
	s_andn2_b64 vcc, exec, s[2:3]
	s_mov_b32 s41, 0
	s_cbranch_vccnz .LBB0_333
	v_readlane_b32 s41, v255, 4
